# speedup vs baseline: 1.0133x; 1.0079x over previous
;   __device__ __forceinline__ bf16* qn() const { return (bf16*)(ws + OFF_qn); }
;   __device__ __forceinline__ float* cmpout() const { return (float*)(ws + OFF_cmpout); }
; __device__ __forceinline__ float bf2f(bf16 h) { return __uint_as_float(((uint32_t)h) << 16); }
; __device__ __forceinline__ int launder(int v) { asm volatile("" : "+v"(v)); return v; }
; __device__ __forceinline__ void attn_phase(const Params& p, int o, char* smem) {
;     ...
;   for (int idx = blockIdx.x; idx < 2048; idx += gridDim.x) {
;     const int tid = launder(tid0), w = tid >> 6, lane = tid & 63, fr = lane & 15, fq = lane >> 4;
;     const int half = idx >> 10, pidx = idx & 1023, bg = pidx >> 5, c5 = pidx & 31;
;     const int cur = half ? 63 - c5 : c5;
;     const int b = bg >> 1, g = bg & 1;
;     const long tokbase = (long)b * SEQ + 64 * cur;
;     bf16x8 Qf[2][2];
;     int pos[2];
;     float gate[2][3];
; #pragma unroll
;     for (int qt = 0; qt < 2; ++qt) {
;       const int tokl = 8 * w + 4 * qt + (fr >> 2), head = fr & 3;
;       const bf16* qp = p.qn() + (tokbase + tokl) * 512 + (4 * g + head) * 64 + 8 * fq;
;       Qf[qt][0] = *(const bf16x8*)qp;
;       Qf[qt][1] = *(const bf16x8*)(qp + 32);
;       pos[qt] = 64 * cur + tokl;
;       const bf16* gp = u + (tokbase + tokl) * ODD_LD + 1280 + (4 * g + head) * 3;
;       gate[qt][0] = sigmoidf_(bf2f(gp[0]));
;       gate[qt][1] = sigmoidf_(bf2f(gp[1]));
;       gate[qt][2] = sigmoidf_(bf2f(gp[2]));
;     }
; #pragma unroll
;     for (int q = 0; q < 8; ++q) {
;       impA[(8 * w + q) * 64 + lane] = 0.f;
;       impB[(8 * w + q) * 64 + lane] = 0.f;
;     }
;     __syncthreads();
;     f32x4 S[4][2], O[4][2], OUT[4][2];
;     float m[2], l[2];
;     uint32_t vm[2];
;     const int ncv = min(255, 4 * cur + 3);
;     const int ntc = (ncv + 63) >> 6;
;     const float* kcb = p.cmpout() + (long)(bg * 256) * 64;
;     const float* vcb = p.cmpout() + (long)(8192 + bg * 256) * 64;
;     m[0] = m[1] = NEGF;
;     l[0] = l[1] = 0.f;
; #pragma unroll
;     for (int dt = 0; dt < 4; ++dt) { O[dt][0] = f32x4{0.f, 0.f, 0.f, 0.f}; O[dt][1] = f32x4{0.f, 0.f, 0.f, 0.f}; }
; #pragma unroll 1
;     for (int ct = 0; ct < ntc; ++ct)
;       attn_stage_cmp((bf16*)(smem + ct * 17920), (bf16*)(smem + ct * 17920 + 9216), kcb + (long)ct * 64 * 64,
;                      vcb + (long)ct * 64 * 64, kn2, tid);
.LBB0_590:
	s_mov_b32 s101, s56
	s_cmpk_lg_u32 s45, 0x100
	s_cbranch_scc1 .Lattn_nomap
	s_lshr_b32 s0, s56, 8
	s_and_b32 s1, s56, 7
	s_bfe_u32 s2, s56, 0x50003
	s_and_b32 s101, s0, 1
	s_sub_u32 s101, 0, s101
	s_and_b32 s101, s101, 7
	s_xor_b32 s1, s1, s101
	s_lshl_b32 s0, s0, 3
	s_or_b32 s0, s0, s1
	s_lshr_b32 s1, s0, 5
	s_sub_u32 s101, 0, s1
	s_and_b32 s101, s101, 63
	s_xor_b32 s0, s0, s101
	s_lshl_b32 s1, s1, 10
	s_lshl_b32 s2, s2, 5
	s_or_b32 s0, s0, s1
	s_or_b32 s101, s0, s2
.Lattn_nomap:
	s_lshl_b32 s0, s101, 11
	s_and_b32 s1, s101, 31
	s_and_b32 s0, s0, 0x1f0000
	s_xor_b32 s2, s1, 63
	v_mov_b32_e32 v219, v218
	s_cmpk_lt_u32 s101, 0x400
	v_readlane_b32 s4, v253, 44
	s_cselect_b32 s62, s1, s2
	s_bfe_u32 s57, s101, 0x10005
	v_readlane_b32 s5, v253, 45
	v_and_b32_e32 v85, 3, v219
	v_ashrrev_i32_e32 v95, 6, v219
	s_mov_b32 s7, s5
	s_waitcnt vmcnt(8)
	v_lshl_or_b32 v2, s57, 2, v85
	v_readlane_b32 s4, v253, 7
	s_lshl_b32 s1, s101, 6
	v_lshlrev_b32_e32 v81, 3, v95
	v_bfe_u32 v83, v219, 2, 2
	v_lshlrev_b32_e32 v152, 7, v2
	v_readlane_b32 s5, v253, 8
	s_and_b32 s63, s1, 0xf000
	s_lshl_b32 s2, s62, 6
	v_or_b32_e32 v24, v81, v83
	s_waitcnt vmcnt(7) lgkmcnt(0)
	v_lshl_add_u64 v[0:1], s[4:5], 0, v[152:153]
	v_readlane_b32 s4, v252, 51
	s_or_b32 s6, s63, s2
	v_ashrrev_i32_e32 v25, 31, v24
	v_readlane_b32 s5, v252, 52
	v_or_b32_e32 v26, 4, v24
	v_lshl_add_u64 v[158:159], s[6:7], 0, v[24:25]
	s_waitcnt vmcnt(2)
	v_mov_b64_e32 v[12:13], s[4:5]
	v_ashrrev_i32_e32 v27, 31, v26
	v_and_b32_e32 v152, 48, v219
	s_waitcnt vmcnt(1)
	v_mul_u32_u24_e32 v14, 3, v2
	v_mad_u64_u32 v[10:11], s[4:5], v158, s53, v[12:13]
	v_lshl_add_u64 v[156:157], v[26:27], 0, s[6:7]
	v_lshl_add_u64 v[8:9], v[0:1], 0, v[152:153]
	v_lshlrev_b64 v[0:1], 10, v[158:159]
	v_mad_i32_i24 v11, v159, s53, v11
	v_lshlrev_b32_e32 v14, 1, v14
	v_mov_b32_e32 v15, v153
	v_lshlrev_b64 v[16:17], 10, v[156:157]
	v_mad_u64_u32 v[12:13], s[4:5], v156, s53, v[12:13]
	v_and_b32_e32 v80, 63, v219
	v_lshl_add_u64 v[4:5], v[8:9], 0, v[0:1]
	v_lshl_add_u64 v[10:11], v[10:11], 0, v[14:15]
	v_lshl_add_u64 v[16:17], v[8:9], 0, v[16:17]
	v_mad_i32_i24 v13, v157, s53, v13
	v_lshlrev_b32_e32 v88, 9, v95
	global_load_dwordx4 v[0:3], v[4:5], off
	s_nop 0
	global_load_dwordx4 v[4:7], v[4:5], off offset:64
	s_nop 0
	global_load_dword v25, v[10:11], off offset:2560
	global_load_ushort v27, v[10:11], off offset:2564
	s_nop 0
	global_load_dwordx4 v[8:11], v[16:17], off
	s_waitcnt vmcnt(5)
	v_lshl_add_u64 v[18:19], v[12:13], 0, v[14:15]
	global_load_dwordx4 v[12:15], v[16:17], off offset:64
	global_load_dword v28, v[18:19], off offset:2560
	global_load_ushort v29, v[18:19], off offset:2564
	v_or_b32_e32 v16, v88, v80
	v_lshlrev_b32_e32 v16, 2, v16
	v_add_u32_e32 v18, 0x16000, v16
	ds_write_b32 v18, v153
	v_add_u32_e32 v18, 0x12100, v16
	ds_write_b32 v18, v153
	v_add_u32_e32 v18, 0x16100, v16
	ds_write_b32 v18, v153
	v_add_u32_e32 v18, 0x12200, v16
	ds_write_b32 v18, v153
	v_add_u32_e32 v18, 0x16200, v16
	ds_write_b32 v18, v153
	v_add_u32_e32 v18, 0x12300, v16
	ds_write_b32 v18, v153
	v_add_u32_e32 v18, 0x16300, v16
	ds_write_b32 v18, v153
	v_add_u32_e32 v18, 0x12400, v16
	ds_write_b32 v18, v153
	v_add_u32_e32 v18, 0x16400, v16
	ds_write_b32 v18, v153
	v_add_u32_e32 v18, 0x12500, v16
	ds_write_b32 v18, v153
	v_add_u32_e32 v18, 0x16500, v16
	ds_write_b32 v18, v153
	v_add_u32_e32 v18, 0x12600, v16
	v_add_u32_e32 v17, 0x12000, v16
	ds_write_b32 v18, v153
	v_add_u32_e32 v18, 0x16600, v16
	v_add_u32_e32 v16, 0x16700, v16
	ds_write_b32 v18, v153
	ds_write2st64_b32 v17, v153, v153 offset1:7
	ds_write_b32 v16, v153
	v_lshlrev_b32_e32 v16, 3, v219
	v_and_b32_e32 v82, 56, v16
	v_readlane_b32 s4, v251, 15
	v_lshlrev_b32_e32 v20, 2, v82
	v_readlane_b32 s5, v251, 16
	s_waitcnt lgkmcnt(0)
	s_barrier
	s_nop 2
	global_load_dwordx4 v[16:19], v20, s[4:5] offset:528
	s_nop 0
	global_load_dwordx4 v[20:23], v20, s[4:5] offset:512
	v_and_b32_e32 v32, 64, v211
	v_xor_b32_e32 v31, 1, v211
	v_add_u32_e32 v96, 64, v32
	v_cmp_lt_i32_e32 vcc, v31, v96
	v_ashrrev_i32_e32 v94, 3, v219
	s_movk_i32 s1, 0x90
	v_cndmask_b32_e32 v31, v211, v31, vcc
	v_lshlrev_b32_e32 v91, 2, v31
	v_xor_b32_e32 v31, 2, v211
	v_cmp_lt_i32_e32 vcc, v31, v96
	v_and_b32_e32 v35, 7, v219
	s_mov_b32 s37, s7
	v_cndmask_b32_e32 v31, v211, v31, vcc
	v_lshlrev_b32_e32 v92, 2, v31
	v_xor_b32_e32 v31, 4, v211
	v_cmp_lt_i32_e32 vcc, v31, v96
	v_lshl_or_b32 v32, v35, 5, s0
	v_mov_b32_e32 v33, v153
	v_cndmask_b32_e32 v31, v211, v31, vcc
	v_lshlrev_b32_e32 v93, 2, v31
	v_mul_lo_u32 v31, v94, s1
	s_lshl_b32 s1, s62, 10
	v_readlane_b32 s4, v253, 22
	v_bfe_u32 v98, v219, 4, 2
	v_mul_u32_u24_e32 v34, 0x88, v82
	s_addk_i32 s1, 0x4200
	v_readlane_b32 s18, v253, 36
	v_readlane_b32 s19, v253, 37
	s_movk_i32 s0, 0x2400
	v_and_b32_e32 v89, 15, v219
	v_lshlrev_b32_e32 v99, 3, v98
	s_and_b32 s3, s1, 0x1c000
	v_lshl_add_u32 v31, v35, 4, v31
	v_readlane_b32 s5, v253, 23
	v_readlane_b32 s6, v253, 24
	s_waitcnt vmcnt(7)
	v_lshlrev_b32_e32 v30, 16, v25
	s_waitcnt vmcnt(6)
	v_lshlrev_b32_e32 v27, 16, v27
	v_mul_f32_e32 v27, 0xbfb8aa3b, v27
	v_exp_f32_e32 v220, v27
	s_waitcnt vmcnt(3)
	v_lshlrev_b32_e32 v27, 16, v28
	v_and_b32_e32 v28, 0xffff0000, v28
	v_mul_f32_e32 v28, 0xbfb8aa3b, v28
	v_and_b32_e32 v25, 0xffff0000, v25
	v_exp_f32_e32 v221, v28
	s_waitcnt vmcnt(2)
	v_lshlrev_b32_e32 v28, 16, v29
	v_mul_f32_e32 v30, 0xbfb8aa3b, v30
	v_mul_f32_e32 v25, 0xbfb8aa3b, v25
	v_mul_f32_e32 v27, 0xbfb8aa3b, v27
	v_mul_f32_e32 v28, 0xbfb8aa3b, v28
	v_exp_f32_e32 v90, v30
	v_exp_f32_e32 v25, v25
	v_exp_f32_e32 v27, v27
	v_exp_f32_e32 v30, v28
	v_lshlrev_b32_e32 v28, 6, v94
	v_ashrrev_i32_e32 v29, 31, v28
	v_lshl_add_u64 v[28:29], v[28:29], 2, v[32:33]
	v_lshlrev_b32_e32 v32, 1, v94
	v_lshl_add_u64 v[28:29], s[18:19], 0, v[28:29]
	v_add3_u32 v32, v34, v32, s0
	s_mov_b64 s[0:1], 0
	v_readlane_b32 s7, v253, 25
	v_readlane_b32 s8, v253, 26
	v_readlane_b32 s9, v253, 27
	v_readlane_b32 s10, v253, 28
	v_readlane_b32 s11, v253, 29
	v_readlane_b32 s12, v253, 30
	v_readlane_b32 s13, v253, 31
	v_readlane_b32 s14, v253, 32
	v_readlane_b32 s15, v253, 33
	v_readlane_b32 s16, v253, 34
	v_readlane_b32 s17, v253, 35

; template <bool BOUNDARY, bool Q0, bool Q1>
; __device__ __forceinline__ void attn_tile(const bf16* Ks, const bf16* Vt, const bf16x8 (&Qf)[2][2], const uint32_t (&vm)[2],
;                                           float (&m)[2], float (&l)[2], f32x4 (&O)[4][2], int fr, int fq) {
;     ...
; #pragma unroll
;   for (int kt = 0; kt < 4; ++kt) {
;     S[kt][0] = f32x4{0.f, 0.f, 0.f, 0.f};
;     S[kt][1] = f32x4{0.f, 0.f, 0.f, 0.f};
; #pragma unroll
;     for (int ks = 0; ks < 2; ++ks) {
;       const bf16x8 kf = *(const bf16x8*)(Ks + (16 * kt + fr) * KS_LD + 32 * ks + 8 * fq);
;       if (Q0) S[kt][0] = __builtin_amdgcn_mfma_f32_16x16x32_bf16(kf, Qf[0][ks], S[kt][0], 0, 0, 0);
;       if (Q1) S[kt][1] = __builtin_amdgcn_mfma_f32_16x16x32_bf16(kf, Qf[1][ks], S[kt][1], 0, 0, 0);
;     }
;   }
; #pragma unroll
;   for (int qt = 0; qt < 2; ++qt) {
;     if ((qt == 0 && !Q0) || (qt == 1 && !Q1)) continue;
;     float mx, mxu;
;     if (BOUNDARY) {
;       mx = m[qt];
; #pragma unroll
;       for (int kt = 0; kt < 4; ++kt)
; #pragma unroll
;         for (int j = 0; j < 4; ++j) {
;           const float s2 = S[kt][qt][j];
;           if ((vm[qt] >> (kt * 4 + j)) & 1u) mx = fmaxf(mx, s2);
;         }
;       mx = fmaxf(mx, __shfl_xor(mx, 16));
;       mx = fmaxf(mx, __shfl_xor(mx, 32));
;       mxu = mx;
;     } else {
;       float rm = -3.0e38f;
; #pragma unroll
;       for (int kt = 0; kt < 4; ++kt)
; #pragma unroll
;         for (int j = 0; j < 4; ++j) {
;           rm = fmaxf(rm, S[kt][qt][j]);
;         }
;       rm = fmaxf(rm, __shfl_xor(rm, 16));
;       rm = fmaxf(rm, __shfl_xor(rm, 32));
;       const bool rv = vm[qt] != 0u;
;       mx = rv ? fmaxf(m[qt], rm) : m[qt];
;       mxu = rv ? mx : 3.0e38f;
;     }
;     const float alpha = __builtin_amdgcn_exp2f(m[qt] - mx);
;     m[qt] = mx;
;     float ls = 0.f;
; #pragma unroll
;     for (int kt = 0; kt < 4; ++kt)
; #pragma unroll
;       for (int j = 0; j < 4; ++j) {
;         float pv;
;         if (BOUNDARY) pv = ((vm[qt] >> (kt * 4 + j)) & 1u) ? __builtin_amdgcn_exp2f(S[kt][qt][j] - mxu) : 0.f;
;         else pv = __builtin_amdgcn_exp2f(S[kt][qt][j] - mxu);
;         S[kt][qt][j] = pv;
;         ls += pv;
;       }
;     l[qt] = l[qt] * alpha + ls;
; #pragma unroll
;     for (int dt = 0; dt < 4; ++dt) {
;       O[dt][qt][0] *= alpha; O[dt][qt][1] *= alpha; O[dt][qt][2] *= alpha; O[dt][qt][3] *= alpha;
;     }
;   }
.LBB0_665:
	s_andn2_b64 vcc, exec, s[8:9]
	s_cbranch_vccnz .LBB0_675
	v_add_u32_e32 v104, v138, v152
	v_add_u32_e32 v100, v104, v230
	ds_read_b128 v[92:95], v100
	v_add_u32_e32 v143, v104, v163
	ds_read_b128 v[104:107], v143 offset:64
	ds_read_b128 v[100:103], v100 offset:64
	ds_read_b128 v[108:111], v143 offset:2368
	v_cmp_ne_u32_e32 vcc, 0, v142
	s_waitcnt lgkmcnt(3)
	v_mfma_f32_16x16x32_bf16 v[96:99], v[92:95], v[0:3], 0
	ds_read_b128 v[144:147], v143 offset:4672
	v_mfma_f32_16x16x32_bf16 v[92:95], v[92:95], v[8:11], 0
	s_waitcnt lgkmcnt(2)
	v_mfma_f32_16x16x32_bf16 v[120:123], v[100:103], v[4:7], v[96:99]
	v_mfma_f32_16x16x32_bf16 v[100:103], v[100:103], v[12:15], v[92:95]
	s_nop 4
	ds_read_b128 v[92:95], v143
	s_waitcnt lgkmcnt(0)
	v_mfma_f32_16x16x32_bf16 v[96:99], v[92:95], v[0:3], 0
	v_mfma_f32_16x16x32_bf16 v[92:95], v[92:95], v[8:11], 0
	v_mfma_f32_16x16x32_bf16 v[116:119], v[104:107], v[4:7], v[96:99]
	v_mfma_f32_16x16x32_bf16 v[96:99], v[104:107], v[12:15], v[92:95]
	s_nop 5
	ds_read_b128 v[92:95], v143 offset:2304
	s_waitcnt lgkmcnt(0)
	v_mfma_f32_16x16x32_bf16 v[104:107], v[92:95], v[0:3], 0
	v_mfma_f32_16x16x32_bf16 v[112:115], v[108:111], v[4:7], v[104:107]
	s_nop 6
	ds_read_b128 v[104:107], v143 offset:4608
	v_mfma_f32_16x16x32_bf16 v[92:95], v[92:95], v[8:11], 0
	v_max3_f32 v143, v120, s49, v121
	v_max3_f32 v143, v143, v122, v123
	v_max3_f32 v143, v143, v116, v117
	v_mfma_f32_16x16x32_bf16 v[92:95], v[108:111], v[12:15], v[92:95]
	v_max3_f32 v143, v143, v118, v119
	v_max3_f32 v143, v143, v112, v113
	v_max3_f32 v143, v143, v114, v115
	s_waitcnt lgkmcnt(0)
	v_mfma_f32_16x16x32_bf16 v[108:111], v[104:107], v[0:3], 0
	v_mfma_f32_16x16x32_bf16 v[108:111], v[144:147], v[4:7], v[108:111]
	v_mfma_f32_16x16x32_bf16 v[104:107], v[104:107], v[8:11], 0
	v_mfma_f32_16x16x32_bf16 v[104:107], v[144:147], v[12:15], v[104:107]
	s_nop 5
	v_max3_f32 v143, v143, v108, v109
	v_max3_f32 v143, v143, v110, v111
	v_max3_f32 v144, v100, s49, v101
	v_max3_f32 v144, v144, v102, v103
	v_max3_f32 v144, v144, v96, v97
	v_max3_f32 v144, v144, v98, v99
	v_max3_f32 v144, v144, v92, v93
	v_max3_f32 v144, v144, v94, v95
	v_max3_f32 v144, v144, v104, v105
	v_max3_f32 v144, v144, v106, v107
	ds_bpermute_b32 v145, v225, v143
	ds_bpermute_b32 v146, v225, v144
	s_waitcnt lgkmcnt(1)
	v_max_f32_e32 v145, v145, v145
	v_max_f32_e32 v143, v143, v145
	s_waitcnt lgkmcnt(0)
	v_max_f32_e32 v146, v146, v146
	v_max_f32_e32 v144, v144, v146
	ds_bpermute_b32 v145, v224, v143
	ds_bpermute_b32 v146, v224, v144
	v_mov_b32_e32 v142, 0x7f61b1e6
	s_waitcnt lgkmcnt(1)
	v_max3_f32 v145, v141, v143, v145
	v_cndmask_b32_e32 v143, v141, v145, vcc
	v_cndmask_b32_e32 v142, v142, v143, vcc
	v_cmp_ne_u32_e32 vcc, 0, v140
	v_mov_b32_e32 v140, 0x7f61b1e6
	s_waitcnt lgkmcnt(0)
	v_max3_f32 v146, v139, v144, v146
	v_cndmask_b32_e32 v144, v139, v146, vcc
	s_nop 0
	v_cndmask_b32_e32 v140, v140, v144, vcc
	v_sub_f32_e32 v120, v120, v142
	v_exp_f32_e32 v120, v120
	v_sub_f32_e32 v121, v121, v142
	v_exp_f32_e32 v121, v121
	v_sub_f32_e32 v122, v122, v142
	v_exp_f32_e32 v122, v122
	v_sub_f32_e32 v123, v123, v142
	v_exp_f32_e32 v123, v123
	v_sub_f32_e32 v116, v116, v142
	v_add_f32_e32 v145, 0, v120
	v_exp_f32_e32 v116, v116
	v_sub_f32_e32 v117, v117, v142
	v_add_f32_e32 v145, v121, v145
	v_exp_f32_e32 v117, v117
	v_sub_f32_e32 v118, v118, v142
	v_add_f32_e32 v145, v122, v145
	v_exp_f32_e32 v118, v118
	v_sub_f32_e32 v119, v119, v142
	v_add_f32_e32 v145, v123, v145
	v_exp_f32_e32 v119, v119
	v_sub_f32_e32 v112, v112, v142
	v_add_f32_e32 v145, v116, v145
	v_exp_f32_e32 v112, v112
	v_sub_f32_e32 v113, v113, v142
	v_add_f32_e32 v145, v117, v145
	v_exp_f32_e32 v113, v113
	v_sub_f32_e32 v114, v114, v142
	v_add_f32_e32 v145, v118, v145
	v_exp_f32_e32 v114, v114
	v_sub_f32_e32 v115, v115, v142
	v_add_f32_e32 v145, v119, v145
	v_exp_f32_e32 v115, v115
	v_sub_f32_e32 v108, v108, v142
	v_add_f32_e32 v145, v112, v145
	v_exp_f32_e32 v147, v108
	v_sub_f32_e32 v109, v109, v142
	v_add_f32_e32 v145, v113, v145
	v_exp_f32_e32 v109, v109
	v_sub_f32_e32 v110, v110, v142
	v_add_f32_e32 v145, v114, v145
	v_exp_f32_e32 v110, v110
	v_sub_f32_e32 v111, v111, v142
	v_add_f32_e32 v145, v115, v145
	v_exp_f32_e32 v111, v111
	v_add_f32_e32 v108, v147, v145
	v_add_f32_e32 v108, v109, v108
	v_sub_f32_e32 v141, v141, v143
	v_add_f32_e32 v108, v110, v108
	v_sub_f32_e32 v100, v100, v140
	v_add_f32_e32 v145, v111, v108
	v_exp_f32_e32 v108, v141
	v_exp_f32_e32 v100, v100
	v_sub_f32_e32 v101, v101, v140
	v_exp_f32_e32 v101, v101
	v_sub_f32_e32 v102, v102, v140
	v_exp_f32_e32 v102, v102
	v_sub_f32_e32 v103, v103, v140
	v_exp_f32_e32 v103, v103
	v_sub_f32_e32 v96, v96, v140
	v_fmac_f32_e32 v145, v132, v108
	v_pk_mul_f32 v[90:91], v[90:91], v[108:109] op_sel_hi:[1,0]
	v_pk_mul_f32 v[88:89], v[88:89], v[108:109] op_sel_hi:[1,0]
	v_pk_mul_f32 v[86:87], v[86:87], v[108:109] op_sel_hi:[1,0]
	v_pk_mul_f32 v[84:85], v[84:85], v[108:109] op_sel_hi:[1,0]
	v_pk_mul_f32 v[82:83], v[82:83], v[108:109] op_sel_hi:[1,0]
	v_pk_mul_f32 v[80:81], v[80:81], v[108:109] op_sel_hi:[1,0]
	v_pk_mul_f32 v[78:79], v[78:79], v[108:109] op_sel_hi:[1,0]
	v_pk_mul_f32 v[76:77], v[76:77], v[108:109] op_sel_hi:[1,0]
	v_sub_f32_e32 v108, v139, v144
	v_add_f32_e32 v132, 0, v100
	v_exp_f32_e32 v139, v96
	v_add_f32_e32 v132, v101, v132
	v_add_f32_e32 v132, v102, v132
	v_add_f32_e32 v132, v103, v132
	v_sub_f32_e32 v97, v97, v140
	v_add_f32_e32 v96, v139, v132
	v_exp_f32_e32 v132, v97
	v_sub_f32_e32 v97, v98, v140
	v_exp_f32_e32 v141, v97
	v_sub_f32_e32 v97, v99, v140
	v_exp_f32_e32 v99, v97
	v_sub_f32_e32 v92, v92, v140
	v_exp_f32_e32 v142, v92
	v_sub_f32_e32 v93, v93, v140
	v_add_f32_e32 v96, v132, v96
	v_exp_f32_e32 v148, v93
	v_sub_f32_e32 v93, v94, v140
	v_add_f32_e32 v96, v141, v96
	v_exp_f32_e32 v149, v93
	v_sub_f32_e32 v93, v95, v140
	v_add_f32_e32 v96, v99, v96
	v_exp_f32_e32 v150, v93
	v_sub_f32_e32 v93, v104, v140
	v_add_f32_e32 v92, v142, v96
	v_exp_f32_e32 v104, v93
	v_sub_f32_e32 v93, v105, v140
	v_add_f32_e32 v92, v148, v92
	v_exp_f32_e32 v105, v93
	v_sub_f32_e32 v93, v106, v140
	v_add_f32_e32 v92, v149, v92
	v_exp_f32_e32 v106, v93
	v_sub_f32_e32 v93, v107, v140
	v_add_f32_e32 v92, v150, v92
	v_exp_f32_e32 v107, v93
	v_add_f32_e32 v92, v104, v92
	v_add_f32_e32 v92, v105, v92
	v_add_f32_e32 v92, v106, v92
	s_waitcnt lgkmcnt(0)
; template <bool BOUNDARY, bool Q0, bool Q1>
; __device__ __forceinline__ void attn_tile(const bf16* Ks, const bf16* Vt, const bf16x8 (&Qf)[2][2], const uint32_t (&vm)[2],
;                                           float (&m)[2], float (&l)[2], f32x4 (&O)[4][2], int fr, int fq) {
;     ...
;     l[qt] = l[qt] * alpha + ls;
; #pragma unroll
;     for (int dt = 0; dt < 4; ++dt) {
;       O[dt][qt][0] *= alpha; O[dt][qt][1] *= alpha; O[dt][qt][2] *= alpha; O[dt][qt][3] *= alpha;
;     }
;   }
; #pragma unroll
;   for (int kp = 0; kp < 2; ++kp) {
;     bf16x8 Pf[2];
; #pragma unroll
;     for (int qt = 0; qt < 2; ++qt) {
;       const u32x4 pk = {pack2(S[2 * kp][qt][0], S[2 * kp][qt][1]), pack2(S[2 * kp][qt][2], S[2 * kp][qt][3]),
;                         pack2(S[2 * kp + 1][qt][0], S[2 * kp + 1][qt][1]), pack2(S[2 * kp + 1][qt][2], S[2 * kp + 1][qt][3])};
;       Pf[qt] = __builtin_bit_cast(bf16x8, pk);
;     }
; #pragma unroll
;     for (int dt = 0; dt < 4; ++dt) {
;       const bf16x4 v0 = *(const bf16x4*)(Vt + (16 * dt + fr) * VT_LD + 32 * kp + 4 * fq);
;       const bf16x4 v1 = *(const bf16x4*)(Vt + (16 * dt + fr) * VT_LD + 32 * kp + 16 + 4 * fq);
;       bf16x8 vf;
;       vf[0] = v0[0]; vf[1] = v0[1]; vf[2] = v0[2]; vf[3] = v0[3];
;       vf[4] = v1[0]; vf[5] = v1[1]; vf[6] = v1[2]; vf[7] = v1[3];
;       if (Q0) O[dt][0] = __builtin_amdgcn_mfma_f32_16x16x32_bf16(vf, Pf[0], O[dt][0], 0, 0, 0);
;       if (Q1) O[dt][1] = __builtin_amdgcn_mfma_f32_16x16x32_bf16(vf, Pf[1], O[dt][1], 0, 0, 0);
;     }
;   }
	v_add_f32_e32 v146, v107, v92
	v_exp_f32_e32 v92, v108
	v_lshlrev_b32_e32 v108, 1, v223
	v_cvt_pk_bf16_f32 v96, v100, v101
	v_add3_u32 v100, v138, v231, v108
	v_fmac_f32_e32 v146, v133, v92
	v_pk_mul_f32 v[74:75], v[74:75], v[92:93] op_sel_hi:[1,0]
	v_pk_mul_f32 v[72:73], v[72:73], v[92:93] op_sel_hi:[1,0]
	v_pk_mul_f32 v[70:71], v[70:71], v[92:93] op_sel_hi:[1,0]
	v_pk_mul_f32 v[68:69], v[68:69], v[92:93] op_sel_hi:[1,0]
	v_pk_mul_f32 v[66:67], v[66:67], v[92:93] op_sel_hi:[1,0]
	v_pk_mul_f32 v[64:65], v[64:65], v[92:93] op_sel_hi:[1,0]
	v_pk_mul_f32 v[62:63], v[62:63], v[92:93] op_sel_hi:[1,0]
	v_pk_mul_f32 v[60:61], v[60:61], v[92:93] op_sel_hi:[1,0]
	v_cvt_pk_bf16_f32 v92, v120, v121
	v_add_u32_e32 v120, 0x2000, v100
	v_cvt_pk_bf16_f32 v97, v102, v103
	v_cvt_pk_bf16_f32 v93, v122, v123
	ds_read2_b64 v[100:103], v120 offset0:128 offset1:132
	v_cvt_pk_bf16_f32 v94, v116, v117
	v_cvt_pk_bf16_f32 v95, v118, v119
	v_cvt_pk_bf16_f32 v98, v139, v132
	v_cvt_pk_bf16_f32 v99, v141, v99
	v_lshlrev_b32_e32 v132, 1, v233
	v_add3_u32 v108, v138, v132, v108
	v_add_u32_e32 v121, 0x2000, v108
	v_add_u32_e32 v122, 0x2800, v108
	v_add_u32_e32 v123, 0x3000, v108
	v_cvt_pk_bf16_f32 v116, v112, v113
	v_cvt_pk_bf16_f32 v117, v114, v115
	ds_read2_b64 v[112:115], v122 offset0:144 offset1:148
	v_cvt_pk_bf16_f32 v118, v147, v109
	v_cvt_pk_bf16_f32 v119, v110, v111
	ds_read2_b64 v[108:111], v123 offset0:160 offset1:164
	v_cvt_pk_bf16_f32 v138, v142, v148
	v_cvt_pk_bf16_f32 v139, v149, v150
	v_cvt_pk_bf16_f32 v140, v104, v105
	v_cvt_pk_bf16_f32 v141, v106, v107
	ds_read2_b64 v[104:107], v121 offset0:128 offset1:132
	s_waitcnt lgkmcnt(3)
	v_mfma_f32_16x16x32_bf16 v[88:91], v[100:103], v[92:95], v[88:91]
	v_mfma_f32_16x16x32_bf16 v[72:75], v[100:103], v[96:99], v[72:75]
	ds_read2_b64 v[100:103], v120 offset0:136 offset1:140
	s_waitcnt lgkmcnt(3)
	v_mfma_f32_16x16x32_bf16 v[80:83], v[112:115], v[92:95], v[80:83]
	v_mfma_f32_16x16x32_bf16 v[64:67], v[112:115], v[96:99], v[64:67]
	ds_read2_b64 v[112:115], v122 offset0:152 offset1:156
	s_waitcnt lgkmcnt(3)
	v_mfma_f32_16x16x32_bf16 v[76:79], v[108:111], v[92:95], v[76:79]
	v_mfma_f32_16x16x32_bf16 v[60:63], v[108:111], v[96:99], v[60:63]
	ds_read2_b64 v[108:111], v121 offset0:136 offset1:140
	s_waitcnt lgkmcnt(3)
	v_mfma_f32_16x16x32_bf16 v[84:87], v[104:107], v[92:95], v[84:87]
	v_mfma_f32_16x16x32_bf16 v[68:71], v[104:107], v[96:99], v[68:71]
	ds_read2_b64 v[148:151], v123 offset0:168 offset1:172
	s_waitcnt lgkmcnt(3)
	v_mfma_f32_16x16x32_bf16 v[92:95], v[100:103], v[138:141], v[72:75]
	v_mfma_f32_16x16x32_bf16 v[100:103], v[100:103], v[116:119], v[88:91]
	s_waitcnt lgkmcnt(2)
	v_mfma_f32_16x16x32_bf16 v[104:107], v[112:115], v[138:141], v[64:67]
	v_mfma_f32_16x16x32_bf16 v[112:115], v[112:115], v[116:119], v[80:83]
	s_waitcnt lgkmcnt(1)
	v_mfma_f32_16x16x32_bf16 v[96:99], v[108:111], v[138:141], v[68:71]
	v_mfma_f32_16x16x32_bf16 v[108:111], v[108:111], v[116:119], v[84:87]
	s_waitcnt lgkmcnt(0)
	v_mfma_f32_16x16x32_bf16 v[120:123], v[148:151], v[116:119], v[76:79]
	v_mfma_f32_16x16x32_bf16 v[116:119], v[148:151], v[138:141], v[60:63]
